# combine phase (rwkv/diff outputs -> OB): write-through stores, no L2 write-back at its barrier
# speedup vs baseline: 1.0045x; 1.0045x over previous
.LBB0_3081:
	v_lshl_add_u64 v[22:23], s[14:15], 0, v[12:13]
	v_add_co_u32_e32 v30, vcc, 0xe5a8000, v22
	v_lshl_add_u64 v[20:21], s[14:15], 0, v[10:11]
	s_nop 0
	v_addc_co_u32_e32 v31, vcc, 0, v23, vcc
	v_add_co_u32_e64 v26, s[2:3], s13, v22
	v_add_co_u32_e32 v22, vcc, 0x8528000, v20
	s_nop 0
	v_addc_co_u32_e64 v27, s[2:3], 0, v23, s[2:3]
	v_addc_co_u32_e32 v23, vcc, 0, v21, vcc
	v_add_co_u32_e32 v50, vcc, 0x9128000, v20
	ds_read2_b64 v[2:5], v11 offset0:40 offset1:50
	ds_read_b128 v[6:9], v11 offset:384
	v_addc_co_u32_e32 v51, vcc, 0, v21, vcc
	v_lshl_add_u64 v[38:39], v[20:21], 0, s[18:19]
	global_load_dword v118, v[30:31], off
	global_load_dword v119, v[30:31], off offset:256
	global_load_dword v121, v[30:31], off offset:512
	global_load_dword v122, v[30:31], off offset:768
	global_load_dword v123, v[30:31], off offset:1024
	global_load_dword v125, v[30:31], off offset:1280
	global_load_dword v127, v[30:31], off offset:1536
	global_load_dword v129, v[30:31], off offset:1792
	s_nop 0
	global_load_dwordx4 v[30:33], v[22:23], off
	global_load_dwordx4 v[34:37], v[38:39], off offset:16
	v_add_co_u32_e32 v22, vcc, 0xc928000, v20
	v_lshl_add_u64 v[46:47], v[20:21], 0, s[20:21]
	s_nop 0
	v_addc_co_u32_e32 v23, vcc, 0, v21, vcc
	v_add_co_u32_e32 v80, vcc, 0x7928000, v20
	v_lshl_add_u64 v[48:49], v[20:21], 0, s[22:23]
	s_nop 0
	v_addc_co_u32_e32 v81, vcc, 0, v21, vcc
	global_load_dwordx4 v[38:41], v[50:51], off
	global_load_dwordx4 v[42:45], v[46:47], off offset:16
	s_waitcnt lgkmcnt(1)
	v_readfirstlane_b32 s2, v4
	v_readfirstlane_b32 s3, v5
	s_waitcnt lgkmcnt(0)
	v_readfirstlane_b32 s4, v6
	v_readfirstlane_b32 s5, v7
	v_readfirstlane_b32 s6, v8
	v_readfirstlane_b32 s7, v9
	v_readfirstlane_b32 s8, v2
	v_readfirstlane_b32 s9, v3
	global_load_dwordx4 v[2:5], v[22:23], off
	global_load_dwordx4 v[6:9], v[48:49], off offset:16
	v_add_co_u32_e32 v22, vcc, 0xb128000, v20
	v_lshl_add_u64 v[78:79], v[20:21], 0, s[24:25]
	s_nop 0
	v_addc_co_u32_e32 v23, vcc, 0, v21, vcc
	v_add_co_u32_e32 v96, vcc, 0xbd28000, v20
	v_lshl_add_u64 v[86:87], v[20:21], 0, s[26:27]
	s_nop 0
	v_addc_co_u32_e32 v97, vcc, 0, v21, vcc
	global_load_dwordx4 v[46:49], v1, s[2:3] offset:16
	global_load_dwordx4 v[50:53], v1, s[2:3]
	global_load_dwordx4 v[54:57], v1, s[4:5] offset:16
	global_load_dwordx4 v[58:61], v1, s[4:5]
	global_load_dwordx4 v[62:65], v1, s[6:7] offset:16
	global_load_dwordx4 v[66:69], v1, s[6:7]
	global_load_dwordx2 v[108:109], v28, s[8:9]
	global_load_dwordx2 v[110:111], v28, s[8:9] offset:512
	global_load_dwordx2 v[112:113], v28, s[8:9] offset:1024
	global_load_dwordx2 v[114:115], v28, s[8:9] offset:1536
	global_load_dwordx4 v[70:73], v[80:81], off
	global_load_dwordx4 v[74:77], v[78:79], off offset:16
	s_nop 0
	global_load_dwordx4 v[78:81], v[22:23], off
	global_load_dwordx4 v[82:85], v[86:87], off offset:16
	v_add_co_u32_e32 v22, vcc, 0x6128000, v20
	v_lshl_add_u64 v[94:95], v[20:21], 0, s[28:29]
	s_nop 0
	v_addc_co_u32_e32 v23, vcc, 0, v21, vcc
	v_add_co_u32_e32 v116, vcc, 0x6d28000, v20
	v_lshl_add_u64 v[102:103], v[20:21], 0, s[34:35]
	s_nop 0
	v_addc_co_u32_e32 v117, vcc, 0, v21, vcc
	v_lshl_add_u64 v[106:107], v[20:21], 0, s[36:37]
	global_load_dwordx4 v[86:89], v[96:97], off
	global_load_dwordx4 v[90:93], v[94:95], off offset:16
	s_nop 0
	global_load_dwordx4 v[94:97], v[22:23], off
	global_load_dwordx4 v[98:101], v[102:103], off offset:16
	s_nop 0
	global_load_dwordx4 v[20:23], v[116:117], off
	global_load_dwordx4 v[102:105], v[106:107], off offset:16
	s_add_i32 s10, s10, s12
	v_lshl_add_u64 v[24:25], s[14:15], 0, v[16:17]
	s_add_u32 s14, s14, s16
	s_addc_u32 s15, s15, s17
	s_cmpk_lt_i32 s10, 0x1800
	s_waitcnt vmcnt(33)
	v_lshlrev_b32_e32 v106, 16, v118
	s_waitcnt vmcnt(32)
	v_lshlrev_b32_e32 v116, 16, v119
	v_and_b32_e32 v107, 0xffff0000, v118
	v_and_b32_e32 v117, 0xffff0000, v119
	s_waitcnt vmcnt(31)
	v_lshlrev_b32_e32 v118, 16, v121
	s_waitcnt vmcnt(30)
	v_lshlrev_b32_e32 v120, 16, v122
	v_and_b32_e32 v119, 0xffff0000, v121
	v_and_b32_e32 v121, 0xffff0000, v122
	s_waitcnt vmcnt(29)
	v_lshlrev_b32_e32 v122, 16, v123
	s_waitcnt vmcnt(28)
	v_lshlrev_b32_e32 v124, 16, v125
	v_and_b32_e32 v123, 0xffff0000, v123
	v_and_b32_e32 v125, 0xffff0000, v125
	s_waitcnt vmcnt(27)
	v_lshlrev_b32_e32 v126, 16, v127
	s_waitcnt vmcnt(26)
	v_lshlrev_b32_e32 v128, 16, v129
	v_and_b32_e32 v127, 0xffff0000, v127
	v_and_b32_e32 v129, 0xffff0000, v129
	v_pk_fma_f32 v[106:107], v[14:15], v[116:117], v[106:107] neg_lo:[1,0,0] neg_hi:[1,0,0]
	v_pk_fma_f32 v[116:117], v[14:15], v[120:121], v[118:119] neg_lo:[1,0,0] neg_hi:[1,0,0]
	v_pk_fma_f32 v[118:119], v[14:15], v[124:125], v[122:123] neg_lo:[1,0,0] neg_hi:[1,0,0]
	v_pk_fma_f32 v[120:121], v[14:15], v[128:129], v[126:127] neg_lo:[1,0,0] neg_hi:[1,0,0]
	v_pk_mul_f32 v[122:123], v[106:107], v[106:107]
	v_pk_mul_f32 v[124:125], v[116:117], v[116:117]
	v_pk_mul_f32 v[126:127], v[118:119], v[118:119]
	v_pk_mul_f32 v[128:129], v[120:121], v[120:121]
	s_waitcnt vmcnt(23)
	v_pk_add_f32 v[32:33], v[32:33], v[40:41]
	v_pk_add_f32 v[30:31], v[30:31], v[38:39]
	v_add_f32_e32 v122, v122, v123
	s_waitcnt vmcnt(22)
	v_pk_add_f32 v[36:37], v[36:37], v[44:45]
	v_pk_add_f32 v[34:35], v[34:35], v[42:43]
	v_add_f32_e32 v123, v124, v125
	v_add_f32_e32 v124, v126, v127
	v_add_f32_e32 v125, v128, v129
	v_pk_mul_f32 v[38:39], v[32:33], v[32:33]
	v_pk_mul_f32 v[40:41], v[30:31], v[30:31]
	v_add_f32_dpp v126, v122, v122 quad_perm:[1,0,3,2] row_mask:0xf bank_mask:0xf bound_ctrl:1
	v_pk_mul_f32 v[42:43], v[36:37], v[36:37]
	v_pk_mul_f32 v[44:45], v[34:35], v[34:35]
	v_add_f32_dpp v127, v123, v123 quad_perm:[1,0,3,2] row_mask:0xf bank_mask:0xf bound_ctrl:1
	v_add_f32_dpp v124, v124, v124 quad_perm:[1,0,3,2] row_mask:0xf bank_mask:0xf bound_ctrl:1
	v_add_f32_dpp v125, v125, v125 quad_perm:[1,0,3,2] row_mask:0xf bank_mask:0xf bound_ctrl:1
	v_pk_mov_b32 v[122:123], v[40:41], v[38:39] op_sel:[1,0]
	v_mov_b32_e32 v41, v39
	v_add_f32_dpp v126, v126, v126 quad_perm:[2,3,0,1] row_mask:0xf bank_mask:0xf bound_ctrl:1
	v_mov_b32_e32 v38, v42
	v_mov_b32_e32 v39, v44
	v_mov_b32_e32 v44, v43
	v_add_f32_dpp v127, v127, v127 quad_perm:[2,3,0,1] row_mask:0xf bank_mask:0xf bound_ctrl:1
	v_add_f32_dpp v124, v124, v124 quad_perm:[2,3,0,1] row_mask:0xf bank_mask:0xf bound_ctrl:1
	v_add_f32_dpp v125, v125, v125 quad_perm:[2,3,0,1] row_mask:0xf bank_mask:0xf bound_ctrl:1
	s_waitcnt vmcnt(7)
	v_pk_mul_f32 v[42:43], v[80:81], v[68:69]
	v_pk_add_f32 v[40:41], v[122:123], v[40:41]
	v_add_f32_dpp v68, v126, v126 row_half_mirror row_mask:0xf bank_mask:0xf bound_ctrl:1
	v_pk_mul_f32 v[66:67], v[78:79], v[66:67]
	v_pk_add_f32 v[38:39], v[38:39], v[44:45]
	v_add_f32_dpp v69, v127, v127 row_half_mirror row_mask:0xf bank_mask:0xf bound_ctrl:1
	v_add_f32_dpp v78, v124, v124 row_half_mirror row_mask:0xf bank_mask:0xf bound_ctrl:1
	v_add_f32_dpp v79, v125, v125 row_half_mirror row_mask:0xf bank_mask:0xf bound_ctrl:1
	v_add_f32_e32 v40, v40, v41
	v_add_f32_dpp v41, v68, v68 row_mirror row_mask:0xf bank_mask:0xf bound_ctrl:1
	s_waitcnt vmcnt(5)
	v_pk_mul_f32 v[44:45], v[86:87], v[66:67]
	v_add_f32_dpp v66, v69, v69 row_mirror row_mask:0xf bank_mask:0xf bound_ctrl:1
	v_add_f32_dpp v67, v78, v78 row_mirror row_mask:0xf bank_mask:0xf bound_ctrl:1
	v_add_f32_dpp v68, v79, v79 row_mirror row_mask:0xf bank_mask:0xf bound_ctrl:1
	v_add_f32_e32 v39, v40, v39
	v_readlane_b32 s39, v41, 16
	v_readlane_b32 s42, v41, 48
	v_pk_mul_f32 v[62:63], v[82:83], v[62:63]
	v_readlane_b32 s2, v41, 0
	v_readlane_b32 s3, v41, 32
	v_readlane_b32 s4, v66, 0
	v_readlane_b32 s43, v66, 16
	v_readlane_b32 s5, v66, 32
	v_readlane_b32 s44, v66, 48
	v_readlane_b32 s6, v67, 0
	v_readlane_b32 s45, v67, 16
	v_readlane_b32 s7, v67, 32
	v_readlane_b32 s46, v67, 48
	v_readlane_b32 s47, v68, 16
	v_readlane_b32 s48, v68, 48
	s_waitcnt vmcnt(1)
	v_pk_add_f32 v[22:23], v[96:97], v[22:23]
	v_pk_add_f32 v[20:21], v[94:95], v[20:21]
	s_waitcnt vmcnt(0)
	v_pk_add_f32 v[40:41], v[100:101], v[104:105]
	v_pk_add_f32 v[66:67], v[98:99], v[102:103]
	v_add_f32_e32 v82, v38, v39
	v_mov_b32_e32 v38, s39
	v_mov_b32_e32 v39, s42
	v_pk_mul_f32 v[64:65], v[84:85], v[64:65]
	v_readlane_b32 s8, v68, 0
	v_readlane_b32 s9, v68, 32
	v_mov_b32_e32 v68, s43
	v_mov_b32_e32 v69, s44
	v_mov_b32_e32 v78, s45
	v_mov_b32_e32 v79, s46
	v_mov_b32_e32 v80, s47
	v_mov_b32_e32 v81, s48
	v_pk_add_f32 v[22:23], v[22:23], -2.0 op_sel_hi:[1,0]
	v_pk_add_f32 v[20:21], v[20:21], -2.0 op_sel_hi:[1,0]
	v_pk_add_f32 v[40:41], v[40:41], -2.0 op_sel_hi:[1,0]
	v_pk_add_f32 v[66:67], v[66:67], -2.0 op_sel_hi:[1,0]
	v_add_f32_dpp v82, v82, v82 quad_perm:[1,0,3,2] row_mask:0xf bank_mask:0xf bound_ctrl:1
	v_pk_add_f32 v[38:39], s[2:3], v[38:39]
	v_pk_mul_f32 v[42:43], v[88:89], v[42:43]
	v_pk_mul_f32 v[64:65], v[92:93], v[64:65]
	v_pk_mul_f32 v[62:63], v[90:91], v[62:63]
	v_pk_add_f32 v[68:69], s[4:5], v[68:69]
	v_pk_add_f32 v[78:79], s[6:7], v[78:79]
	v_pk_add_f32 v[80:81], s[8:9], v[80:81]
	v_pk_fma_f32 v[22:23], v[22:23], v[60:61], 2.0 op_sel_hi:[1,1,0]
	v_pk_fma_f32 v[20:21], v[20:21], v[58:59], 2.0 op_sel_hi:[1,1,0]
	v_pk_fma_f32 v[40:41], v[40:41], v[56:57], 2.0 op_sel_hi:[1,1,0]
	v_pk_fma_f32 v[54:55], v[66:67], v[54:55], 2.0 op_sel_hi:[1,1,0]
	v_add_f32_dpp v56, v82, v82 quad_perm:[2,3,0,1] row_mask:0xf bank_mask:0xf bound_ctrl:1
	v_add_f32_e32 v58, v38, v39
	v_mov_b32_e32 v38, v78
	v_mov_b32_e32 v39, v68
	v_mov_b32_e32 v68, v79
	v_pk_mul_f32 v[22:23], v[22:23], v[42:43]
	v_pk_mul_f32 v[20:21], v[20:21], v[44:45]
	v_pk_mul_f32 v[40:41], v[40:41], v[64:65]
	v_pk_mul_f32 v[42:43], v[54:55], v[62:63]
	v_mov_b32_dpp v44, v56 row_half_mirror row_mask:0xf bank_mask:0xf bound_ctrl:1
	v_mov_b32_e32 v57, v80
	v_mov_b32_e32 v45, v81
	v_fmamk_f32 v58, v58, 0x3c000000, v29
	v_pk_add_f32 v[38:39], v[38:39], v[68:69]
	v_pk_mov_b32 v[54:55], v[20:21], v[22:23] op_sel:[1,0]
	v_mov_b32_e32 v21, v23
	v_mov_b32_e32 v22, v40
	v_mov_b32_e32 v23, v42
	v_mov_b32_e32 v42, v41
	v_pk_add_f32 v[40:41], v[56:57], v[44:45]
	v_mul_f32_e32 v44, 0x4b800000, v58
	v_cmp_gt_f32_e32 vcc, s11, v58
	v_pk_fma_f32 v[38:39], v[38:39], s[38:39], v[18:19] op_sel_hi:[1,0,0]
	v_pk_add_f32 v[20:21], v[54:55], v[20:21]
	v_pk_add_f32 v[22:23], v[22:23], v[42:43]
	v_pk_fma_f32 v[40:41], v[40:41], s[40:41], v[18:19] op_sel_hi:[1,1,0]
	v_cndmask_b32_e32 v42, v58, v44, vcc
	v_mul_f32_e32 v43, 0x4b800000, v39
	v_mul_f32_e32 v44, 0x4b800000, v38
	v_cmp_gt_f32_e64 s[2:3], s11, v38
	v_cmp_gt_f32_e64 s[4:5], s11, v39
	v_add_f32_e32 v20, v20, v21
	v_mul_f32_e32 v45, 0x4b800000, v40
	v_cmp_gt_f32_e64 s[6:7], s11, v40
	v_rsq_f32_e32 v42, v42
	v_mul_f32_e32 v21, 0x4b800000, v41
	v_cmp_gt_f32_e64 s[8:9], s11, v41
	v_cndmask_b32_e64 v39, v39, v43, s[4:5]
	v_cndmask_b32_e64 v38, v38, v44, s[2:3]
	v_add_f32_e32 v20, v20, v23
	v_cndmask_b32_e64 v23, v40, v45, s[6:7]
	v_cndmask_b32_e64 v21, v41, v21, s[8:9]
	v_rsq_f32_e32 v39, v39
	v_rsq_f32_e32 v38, v38
	v_rsq_f32_e32 v23, v23
	v_rsq_f32_e32 v21, v21
	v_add_f32_e32 v20, v22, v20
	v_mul_f32_e32 v22, 0x45800000, v42
	v_cndmask_b32_e32 v22, v42, v22, vcc
	v_mul_f32_e32 v40, 0x45800000, v39
	v_mul_f32_e32 v41, 0x45800000, v38
	v_mul_f32_e32 v43, 0x45800000, v23
	v_mul_f32_e32 v22, 0x3f24fd5c, v22
	v_add_f32_dpp v20, v20, v20 quad_perm:[1,0,3,2] row_mask:0xf bank_mask:0xf bound_ctrl:1
	v_mul_f32_e32 v42, 0x45800000, v21
	v_cndmask_b32_e64 v39, v39, v40, s[4:5]
	v_cndmask_b32_e64 v41, v38, v41, s[2:3]
	v_cndmask_b32_e64 v38, v23, v43, s[6:7]
	v_pk_mul_f32 v[22:23], v[106:107], v[22:23] op_sel_hi:[1,0]
	v_add_f32_dpp v20, v20, v20 quad_perm:[2,3,0,1] row_mask:0xf bank_mask:0xf bound_ctrl:1
	v_cndmask_b32_e64 v21, v21, v42, s[8:9]
	v_pk_mul_f32 v[30:31], v[30:31], v[38:39] op_sel_hi:[1,0]
	v_pk_mul_f32 v[32:33], v[32:33], v[38:39] op_sel_hi:[1,0]
	v_pk_mul_f32 v[34:35], v[34:35], v[38:39] op_sel_hi:[1,0]
	v_pk_mul_f32 v[36:37], v[36:37], v[38:39] op_sel_hi:[1,0]
	v_pk_mul_f32 v[22:23], v[108:109], v[22:23]
	v_add_f32_dpp v20, v20, v20 row_half_mirror row_mask:0xf bank_mask:0xf bound_ctrl:1
	v_mul_f32_e32 v40, 0x3f24fd5c, v39
	v_mul_f32_e32 v44, 0x3f24fd5c, v21
	v_pk_mul_f32 v[32:33], v[52:53], v[32:33]
	v_pk_mul_f32 v[30:31], v[50:51], v[30:31]
	v_pk_mul_f32 v[36:37], v[48:49], v[36:37]
	v_pk_mul_f32 v[34:35], v[46:47], v[34:35]
	v_cvt_pk_bf16_f32 v21, v22, v23
	v_mul_f32_e32 v42, 0x3f24fd5c, v41
	v_pk_mul_f32 v[38:39], v[116:117], v[40:41] op_sel_hi:[1,0]
	v_pk_fma_f32 v[2:3], v[2:3], v[20:21], v[30:31] op_sel_hi:[1,0,1]
	v_pk_fma_f32 v[4:5], v[4:5], v[20:21], v[32:33] op_sel_hi:[1,0,1]
	v_pk_fma_f32 v[6:7], v[6:7], v[20:21], v[34:35] op_sel_hi:[1,0,1]
	v_pk_fma_f32 v[8:9], v[8:9], v[20:21], v[36:37] op_sel_hi:[1,0,1]
	v_pk_mul_f32 v[40:41], v[118:119], v[42:43] op_sel_hi:[1,0]
	v_pk_mul_f32 v[42:43], v[120:121], v[44:45] op_sel_hi:[1,0]
	v_pk_mul_f32 v[22:23], v[110:111], v[38:39]
	v_pk_mul_f32 v[4:5], v[72:73], v[4:5]
	v_pk_mul_f32 v[2:3], v[70:71], v[2:3]
	v_pk_mul_f32 v[8:9], v[76:77], v[8:9]
	v_pk_mul_f32 v[6:7], v[74:75], v[6:7]
	v_pk_mul_f32 v[38:39], v[112:113], v[40:41]
	v_pk_mul_f32 v[40:41], v[114:115], v[42:43]
	v_cvt_pk_bf16_f32 v20, v22, v23
	v_cvt_pk_bf16_f32 v2, v2, v3
	v_cvt_pk_bf16_f32 v3, v4, v5
	v_cvt_pk_bf16_f32 v4, v6, v7
	v_cvt_pk_bf16_f32 v5, v8, v9
	global_store_dword v[26:27], v21, off sc1
	v_cvt_pk_bf16_f32 v21, v38, v39
	v_cvt_pk_bf16_f32 v22, v40, v41
	global_store_dword v[26:27], v20, off offset:256 sc1
	global_store_dword v[26:27], v21, off offset:512 sc1
	global_store_dword v[26:27], v22, off offset:768 sc1
	global_store_dwordx4 v[24:25], v[2:5], off sc1
	s_cbranch_scc1 .LBB0_3081
